# RNN tile loop: x staging moved to scan-phase start with next-tile prefetch issued a full tile ahead; hand-written phase A with software-pipelined LDS reads for the conv/gate MFMA chain and folded LDS
# speedup vs baseline: 1.0185x; 1.0024x over previous
.LBB0_109:
	s_or_b64 exec, exec, s[10:11]
	s_lshl_b64 s[20:21], s[0:1], 12
	s_add_u32 s0, s16, s20
	s_addc_u32 s1, s17, s21
	s_add_u32 s0, s0, s6
	s_addc_u32 s1, s1, 0
	s_add_u32 s0, s0, s7
	v_ashrrev_i32_e32 v0, 6, v182
	s_addc_u32 s1, s1, 0
	v_mov_b32_e32 v171, v1
	v_lshlrev_b32_e32 v148, 1, v168
	v_lshl_or_b32 v142, v0, 2, v213
	v_lshl_add_u64 v[146:147], s[0:1], 0, v[170:171]
	v_lshl_add_u64 v[2:3], s[26:27], 0, v[170:171]
	v_add_u32_e32 v171, s52, v148
	v_lshlrev_b32_e32 v0, 4, v0
	s_movk_i32 s6, 0x420
	v_add3_u32 v143, v213, v141, v0
	v_or_b32_e32 v220, v0, v141
	v_lshl_add_u32 v224, v141, 6, s98
	v_mul_lo_u32 v225, v142, s6
	v_mul_lo_u32 v142, v142, s51
	v_lshlrev_b32_e32 v0, 4, v141
	v_mad_u32_u24 v141, v183, s51, v171
	v_mul_lo_u32 v150, v143, s51
	v_add_u32_e32 v226, s99, v142
	v_add_u32_e32 v227, s52, v142
	ds_read_u16 v142, v141
	ds_read_u16 v151, v141 offset:272
	ds_read_u16 v143, v141 offset:544
	ds_read_u16 v153, v141 offset:816
	ds_read_u16 v144, v141 offset:1088
	ds_read_u16 v155, v141 offset:1360
	ds_read_u16 v145, v141 offset:1632
	ds_read_u16 v141, v141 offset:1904
	v_lshlrev_b64 v[184:185], 12, v[168:169]
	v_mad_u32_u24 v152, v183, s51, v252
	s_waitcnt lgkmcnt(4)
	v_perm_b32 v143, v153, v143, s8
	s_waitcnt lgkmcnt(2)
	v_perm_b32 v144, v155, v144, s8
	s_waitcnt lgkmcnt(0)
	v_perm_b32 v145, v141, v145, s8
	v_mov_b32_e32 v141, s99
	v_mad_u32_u24 v141, v183, s51, v141
	v_perm_b32 v142, v151, v142, s8
	v_lshl_add_u64 v[146:147], v[146:147], 0, v[184:185]
	v_add_u32_e32 v175, v141, v148
	global_store_dwordx4 v[146:147], v[142:145], off
	ds_write_b16 v175, v120
	ds_write_b16_d16_hi v175, v120 offset:272
	v_add_u32_e32 v120, s99, v152
	v_add_u32_e32 v200, s99, v148
	v_mad_u32_u24 v154, v183, s51, v194
	v_add_u32_e32 v141, v200, v152
	v_add_u32_e32 v201, v120, v148
	v_mad_u32_u24 v156, v183, s51, v195
	ds_write_b16 v141, v121
	ds_write_b16_d16_hi v201, v121 offset:272
	v_add_u32_e32 v120, s99, v154
	v_add_u32_e32 v121, v200, v154
	ds_write_b16 v121, v122
	v_add_u32_e32 v202, v120, v148
	v_add_u32_e32 v120, s99, v156
	v_add_u32_e32 v121, v200, v156
	v_and_b32_e32 v149, 48, v182
	ds_write_b16 v121, v123
	v_add_u32_e32 v203, v120, v148
	v_lshlrev_b64 v[120:121], 11, v[168:169]
	v_lshl_add_u64 v[120:121], v[2:3], 0, v[120:121]
	s_mov_b32 s6, 0x40000
	v_add_u32_e32 v141, 0, v149
	ds_write_b16_d16_hi v202, v122 offset:272
	ds_write_b16_d16_hi v203, v123 offset:272
	v_add_co_u32_e32 v120, vcc, s6, v120
	v_add_u32_e32 v204, 0x19c00, v141
	s_nop 0
	v_addc_co_u32_e32 v121, vcc, 0, v121, vcc
	ds_read_b128 v[142:145], v204
	global_load_dwordx4 v[120:123], v[120:121], off
	v_add_u32_e32 v205, 0, v150
	ds_read_b128 v[146:149], v204 offset:64
	ds_read_b128 v[150:153], v205
	ds_read_b128 v[154:157], v205 offset:16
	ds_read_b128 v[158:161], v205 offset:32
	ds_read_b128 v[162:165], v205 offset:48
	s_waitcnt lgkmcnt(3)
	v_mfma_f32_16x16x32_bf16 v[142:145], v[4:7], v[150:153], v[142:145]
	s_cmp_eq_u32 s28, 0
	s_cselect_b64 vcc, -1, 0
	s_cmp_eq_u32 s28, 1
	s_waitcnt lgkmcnt(1)
	v_mfma_f32_16x16x32_bf16 v[146:149], v[12:15], v[158:161], v[146:149]
	s_cselect_b64 s[40:41], -1, 0
	s_cmp_eq_u32 s28, 2
	s_cselect_b64 s[42:43], -1, 0
	v_mfma_f32_16x16x32_bf16 v[142:145], v[8:11], v[154:157], v[142:145]
	s_cmp_eq_u32 s28, 3
	s_cselect_b64 s[44:45], -1, 0
	s_add_i32 s6, 0, 0x19800
	s_waitcnt lgkmcnt(0)
	v_mfma_f32_16x16x32_bf16 v[146:149], v[16:19], v[162:165], v[146:149]
	v_add_u32_e32 v224, v224, v225
	s_nop 1
	v_cvt_pk_bf16_f32 v142, v142, v143
	v_cvt_pk_bf16_f32 v143, v144, v145
	v_cndmask_b32_e32 v167, 0, v142, vcc
	v_cndmask_b32_e32 v190, 0, v143, vcc
	s_nop 0
	v_cvt_pk_bf16_f32 v144, v146, v147
	v_cvt_pk_bf16_f32 v145, v148, v149
	v_cndmask_b32_e32 v141, 0, v144, vcc
	v_cndmask_b32_e32 v166, 0, v145, vcc
	v_mfma_f32_16x16x32_bf16 v[146:149], v[52:55], v[142:145], 0
	v_add_u32_e32 v226, v226, v0
	v_add_u32_e32 v227, v227, v0
	v_mfma_f32_16x16x32_bf16 v[150:153], v[68:71], v[142:145], 0
	v_mfma_f32_16x16x32_bf16 v[154:157], v[84:87], v[142:145], 0
	v_mfma_f32_16x16x32_bf16 v[158:161], v[100:103], v[142:145], 0
	ds_read_b128 v[142:145], v204 offset:128
	ds_read_b128 v[162:165], v205 offset:64
	ds_read_b128 v[206:209], v205 offset:80
	ds_read_b128 v[228:231], v204 offset:192
	ds_read_b128 v[238:241], v205 offset:96
	ds_read_b128 v[242:245], v205 offset:112
	s_waitcnt lgkmcnt(4)
	v_mfma_f32_16x16x32_bf16 v[142:145], v[20:23], v[162:165], v[142:145]
	s_waitcnt lgkmcnt(1)
	v_mfma_f32_16x16x32_bf16 v[162:165], v[28:31], v[238:241], v[228:231]
	v_mfma_f32_16x16x32_bf16 v[142:145], v[24:27], v[206:209], v[142:145]
	s_waitcnt lgkmcnt(0)
	v_mfma_f32_16x16x32_bf16 v[162:165], v[32:35], v[242:245], v[162:165]
	s_nop 5
	v_cvt_pk_bf16_f32 v142, v142, v143
	v_cvt_pk_bf16_f32 v143, v144, v145
	v_cvt_pk_bf16_f32 v144, v162, v163
	v_cvt_pk_bf16_f32 v145, v164, v165
	v_cndmask_b32_e64 v166, v166, v145, s[40:41]
	v_cndmask_b32_e64 v141, v141, v144, s[40:41]
	v_mfma_f32_16x16x32_bf16 v[146:149], v[56:59], v[142:145], v[146:149]
	v_cndmask_b32_e64 v190, v190, v143, s[40:41]
	v_cndmask_b32_e64 v167, v167, v142, s[40:41]
	v_mfma_f32_16x16x32_bf16 v[150:153], v[72:75], v[142:145], v[150:153]
	v_mfma_f32_16x16x32_bf16 v[154:157], v[88:91], v[142:145], v[154:157]
	v_mfma_f32_16x16x32_bf16 v[158:161], v[104:107], v[142:145], v[158:161]
	ds_read_b128 v[142:145], v204 offset:256
	ds_read_b128 v[162:165], v205 offset:128
	ds_read_b128 v[206:209], v205 offset:144
	ds_read_b128 v[228:231], v204 offset:320
	ds_read_b128 v[238:241], v205 offset:160
	ds_read_b128 v[242:245], v205 offset:176
	s_waitcnt lgkmcnt(4)
	v_mfma_f32_16x16x32_bf16 v[142:145], v[36:39], v[162:165], v[142:145]
	s_waitcnt lgkmcnt(1)
	v_mfma_f32_16x16x32_bf16 v[162:165], v[44:47], v[238:241], v[228:231]
	v_mfma_f32_16x16x32_bf16 v[142:145], v[40:43], v[206:209], v[142:145]
	v_add_u32_e32 v206, 0x21a00, v140
	v_add_u32_e32 v207, 0x22200, v140
	s_waitcnt lgkmcnt(0)
	v_mfma_f32_16x16x32_bf16 v[162:165], v[48:51], v[242:245], v[162:165]
	s_nop 3
	v_cvt_pk_bf16_f32 v142, v142, v143
	v_cvt_pk_bf16_f32 v143, v144, v145
	s_nop 1
	v_cvt_pk_bf16_f32 v144, v162, v163
	v_cvt_pk_bf16_f32 v145, v164, v165
	v_cndmask_b32_e64 v141, v141, v144, s[42:43]
	v_cndmask_b32_e64 v166, v166, v145, s[42:43]
	v_mfma_f32_16x16x32_bf16 v[146:149], v[60:63], v[142:145], v[146:149]
	v_mfma_f32_16x16x32_bf16 v[162:165], v[76:79], v[142:145], v[150:153]
	v_mfma_f32_16x16x32_bf16 v[228:231], v[92:95], v[142:145], v[154:157]
	v_mfma_f32_16x16x32_bf16 v[156:159], v[108:111], v[142:145], v[158:161]
	s_nop 2
	v_cndmask_b32_e64 v160, v167, v142, s[42:43]
	v_cndmask_b32_e64 v161, v190, v143, s[42:43]
	ds_read_b128 v[142:145], v204 offset:384
	ds_read_b128 v[150:153], v205 offset:192
	ds_read_b128 v[238:241], v205 offset:208
	ds_read_b128 v[208:211], v204 offset:448
	ds_read_b128 v[242:245], v205 offset:224
	ds_read_b128 v[246:249], v205 offset:240
	ds_read_b128 v[190:193], v206
	s_waitcnt lgkmcnt(0)
	v_mfma_f32_16x16x32_bf16 v[142:145], v[190:193], v[150:153], v[142:145]
	ds_read_b128 v[150:153], v207
	s_waitcnt lgkmcnt(0)
	v_mfma_f32_16x16x32_bf16 v[150:153], v[150:153], v[242:245], v[208:211]
	s_nop 2
	v_add_u32_e32 v208, 0x21e00, v140
	ds_read_b128 v[190:193], v208
	v_add_u32_e32 v209, 0x22600, v140
	s_waitcnt lgkmcnt(0)
	v_mfma_f32_16x16x32_bf16 v[142:145], v[190:193], v[238:241], v[142:145]
	ds_read_b128 v[190:193], v209
	s_waitcnt lgkmcnt(0)
	v_mfma_f32_16x16x32_bf16 v[150:153], v[190:193], v[246:249], v[150:153]
	s_nop 4
	v_cvt_pk_bf16_f32 v190, v142, v143
	v_cvt_pk_bf16_f32 v191, v144, v145
	s_nop 0
	v_cvt_pk_bf16_f32 v192, v150, v151
	v_cvt_pk_bf16_f32 v193, v152, v153
	v_cndmask_b32_e64 v219, v141, v192, s[44:45]
	v_cndmask_b32_e64 v218, v166, v193, s[44:45]
	v_mfma_f32_16x16x32_bf16 v[140:143], v[112:115], v[190:193], v[156:159]
	s_nop 2
	v_cndmask_b32_e64 v156, v161, v191, s[44:45]
	v_lshlrev_b32_e32 v215, 16, v156
	v_and_b32_e32 v216, 0xffff0000, v156
	v_lshlrev_b32_e32 v156, 2, v217
	v_add_u32_e32 v210, s6, v156
	v_mfma_f32_16x16x32_bf16 v[152:155], v[64:67], v[190:193], v[146:149]
	v_add_u32_e32 v211, s53, v156
	v_cndmask_b32_e64 v157, v160, v190, s[44:45]
	v_add_u32_e32 v212, s54, v156
	v_mfma_f32_16x16x32_bf16 v[144:147], v[80:83], v[190:193], v[162:165]
	v_lshlrev_b32_e32 v221, 16, v157
	v_and_b32_e32 v214, 0xffff0000, v157
	ds_read_b128 v[156:159], v212
	ds_read_b128 v[164:167], v210
	ds_read_b128 v[160:163], v211
	v_mfma_f32_16x16x32_bf16 v[148:151], v[96:99], v[190:193], v[228:231]
	s_waitcnt lgkmcnt(1)
	v_add_f32_e32 v152, v152, v164
	v_exp_f32_e32 v152, v152
	v_and_b32_e32 v164, 0xffff0000, v219
	s_waitcnt lgkmcnt(0)
	s_nop 2
	v_add_f32_e32 v148, v148, v160
	v_exp_f32_e32 v148, v148
	v_add_f32_e32 v152, 1.0, v152
	v_rcp_f32_e64 v152, -v152
	v_add_f32_e32 v149, v149, v161
	v_add_f32_e32 v148, 1.0, v148
	v_rcp_f32_e32 v148, v148
	v_mul_f32_e32 v152, v156, v152
	v_exp_f32_e32 v190, v152
	v_exp_f32_e32 v149, v149
	v_mul_f32_e32 v148, v148, v221
	v_or_b32_e32 v161, 16, v217
	v_fma_f32 v152, -v190, v190, 1.0
	v_max_f32_e32 v152, 0, v152
	v_sqrt_f32_e32 v152, v152
	v_add_f32_e32 v149, 1.0, v149
	v_rcp_f32_e32 v149, v149
	v_mul_f32_e32 v191, v148, v152
	v_mul_u32_u24_e32 v148, 0x210, v213
	v_add_lshl_u32 v160, v220, v148, 3
	v_add_f32_e32 v148, v153, v165
	v_exp_f32_e32 v148, v148
	v_mul_f32_e32 v149, v149, v214
	v_add_u32_e32 v213, s98, v160
	ds_write_b64 v213, v[190:191]
	v_add_f32_e32 v148, 1.0, v148
	v_rcp_f32_e64 v148, -v148
	v_lshlrev_b32_e32 v165, 16, v218
	v_mul_f32_e32 v148, v157, v148
	v_exp_f32_e32 v148, v148
	s_nop 0
	v_fma_f32 v152, -v148, v148, 1.0
	v_max_f32_e32 v152, 0, v152
	v_sqrt_f32_e32 v152, v152
	s_nop 0
	v_mul_f32_e32 v149, v149, v152
	v_add_u32_e32 v152, 0x420, v160
	v_add_u32_e32 v214, s98, v152
	ds_write_b64 v214, v[148:149]
	v_add_f32_e32 v148, v154, v166
	v_exp_f32_e32 v148, v148
	v_add_f32_e32 v149, v150, v162
	v_exp_f32_e32 v149, v149
	v_and_b32_e32 v166, 0xffff0000, v218
	v_add_f32_e32 v148, 1.0, v148
	v_rcp_f32_e64 v148, -v148
	v_add_f32_e32 v149, 1.0, v149
	v_rcp_f32_e32 v149, v149
	v_mul_f32_e32 v148, v158, v148
	v_exp_f32_e32 v148, v148
	v_mul_f32_e32 v149, v149, v215
	v_fma_f32 v150, -v148, v148, 1.0
	v_max_f32_e32 v150, 0, v150
	v_sqrt_f32_e32 v150, v150
	s_nop 0
	v_mul_f32_e32 v149, v149, v150
	v_add_u32_e32 v150, 0x840, v160
	v_add_u32_e32 v215, s98, v150
	ds_write_b64 v215, v[148:149]
	v_add_f32_e32 v148, v155, v167
	v_exp_f32_e32 v148, v148
	v_add_f32_e32 v149, v151, v163
	v_exp_f32_e32 v149, v149
	v_lshlrev_b32_e32 v163, 16, v219
	v_add_f32_e32 v148, 1.0, v148
	v_rcp_f32_e64 v148, -v148
	v_add_f32_e32 v149, 1.0, v149
	v_rcp_f32_e32 v149, v149
	v_mul_f32_e32 v148, v159, v148
	v_exp_f32_e32 v148, v148
	v_mul_f32_e32 v149, v149, v216
	v_fma_f32 v150, -v148, v148, 1.0
	v_max_f32_e32 v150, 0, v150
	v_sqrt_f32_e32 v150, v150
	s_nop 0
	v_mul_f32_e32 v149, v149, v150
	v_add_u32_e32 v150, 0xc60, v160
	v_add_u32_e32 v216, s98, v150
	ds_write_b64 v216, v[148:149]
	v_lshlrev_b32_e32 v148, 2, v161
	v_add_u32_e32 v217, s6, v148
	ds_read_b128 v[156:159], v217
	v_add_u32_e32 v218, s53, v148
	ds_read_b128 v[152:155], v218
	v_add_u32_e32 v219, s54, v148
	ds_read_b128 v[148:151], v219
	s_waitcnt lgkmcnt(2)
	v_add_f32_e32 v144, v144, v156
	v_exp_f32_e32 v144, v144
	s_waitcnt lgkmcnt(1)
	v_add_f32_e32 v140, v140, v152
	v_exp_f32_e32 v140, v140
	v_add_f32_e32 v141, v141, v153
	v_add_f32_e32 v144, 1.0, v144
	v_rcp_f32_e64 v144, -v144
	v_add_f32_e32 v140, 1.0, v140
	v_rcp_f32_e32 v140, v140
	v_exp_f32_e32 v141, v141
	s_waitcnt lgkmcnt(0)
	v_mul_f32_e32 v144, v148, v144
	v_exp_f32_e32 v162, v144
	v_mul_f32_e32 v140, v140, v163
	v_add_f32_e32 v141, 1.0, v141
	v_rcp_f32_e32 v141, v141
	v_fma_f32 v144, -v162, v162, 1.0
	v_max_f32_e32 v144, 0, v144
	v_sqrt_f32_e32 v144, v144
	v_mul_f32_e32 v141, v141, v164
	v_mul_f32_e32 v163, v140, v144
	v_mul_u32_u24_e32 v140, 0x84, v161
	v_add_lshl_u32 v140, v140, v220, 3
	v_add_u32_e32 v220, s98, v140
	v_add_f32_e32 v140, v145, v157
	v_exp_f32_e32 v140, v140
	ds_write_b64 v220, v[162:163]
	v_mov_b32_e32 v161, v1
	v_add_f32_e32 v140, 1.0, v140
	v_rcp_f32_e64 v140, -v140
	s_nop 0
	v_mul_f32_e32 v140, v149, v140
	v_exp_f32_e32 v140, v140
	s_nop 0
	v_fma_f32 v144, -v140, v140, 1.0
	v_max_f32_e32 v144, 0, v144
	v_sqrt_f32_e32 v144, v144
	s_nop 0
	v_mul_f32_e32 v141, v141, v144
	v_add_u32_e32 v144, 0x4620, v160
	v_add_u32_e32 v221, s98, v144
	ds_write_b64 v221, v[140:141]
	v_add_f32_e32 v140, v146, v158
	v_exp_f32_e32 v140, v140
	v_add_f32_e32 v141, v142, v154
	v_exp_f32_e32 v141, v141
	v_add_f32_e32 v140, 1.0, v140
	v_rcp_f32_e64 v140, -v140
	v_add_f32_e32 v141, 1.0, v141
	v_rcp_f32_e32 v141, v141
	v_mul_f32_e32 v140, v150, v140
	v_exp_f32_e32 v140, v140
	v_mul_f32_e32 v141, v141, v165
	v_fma_f32 v142, -v140, v140, 1.0
	v_max_f32_e32 v142, 0, v142
	v_sqrt_f32_e32 v142, v142
	s_nop 0
	v_mul_f32_e32 v141, v141, v142
	v_add_u32_e32 v142, 0x4a40, v160
	v_add_u32_e32 v222, s98, v142
	ds_write_b64 v222, v[140:141]
	v_add_f32_e32 v140, v147, v159
	v_exp_f32_e32 v140, v140
	v_add_f32_e32 v141, v143, v155
	v_exp_f32_e32 v141, v141
	v_add_f32_e32 v140, 1.0, v140
	v_rcp_f32_e64 v140, -v140
	v_add_f32_e32 v141, 1.0, v141
	v_rcp_f32_e32 v141, v141
	v_mul_f32_e32 v140, v151, v140
	v_exp_f32_e32 v140, v140
	v_mul_f32_e32 v141, v141, v166
	v_fma_f32 v142, -v140, v140, 1.0
	v_max_f32_e32 v142, 0, v142
	v_sqrt_f32_e32 v142, v142
	s_nop 0
	v_mul_f32_e32 v141, v141, v142
	v_add_u32_e32 v142, 0x4e60, v160
	v_add_u32_e32 v223, s98, v142
	ds_write_b64 v223, v[140:141]
	s_waitcnt lgkmcnt(0)
	s_barrier
	ds_read_b128 v[148:151], v224
	ds_read_b128 v[152:155], v224 offset:16
	ds_read_b128 v[144:147], v224 offset:32
	ds_read_b128 v[140:143], v224 offset:48
	s_waitcnt lgkmcnt(3)
	v_fma_f32 v149, 0, v148, v149
	v_fma_f32 v156, v150, v149, v151
	v_mul_f32_e32 v157, v148, v150
	s_waitcnt lgkmcnt(2)
	v_fma_f32 v158, v152, v156, v153
	v_mul_f32_e32 v159, v157, v152
	v_mul_f32_e32 v160, v154, v159
	v_fmac_f32_e32 v155, v154, v158
	s_waitcnt lgkmcnt(1)
	v_fma_f32 v145, v144, v155, v145
	v_mul_f32_e32 v144, v144, v160
	v_mul_f32_e32 v154, v146, v144
	v_fmac_f32_e32 v147, v146, v145
	s_waitcnt lgkmcnt(0)
	v_fma_f32 v141, v140, v147, v141
	v_mul_f32_e32 v140, v140, v154
	v_mul_f32_e32 v146, v142, v140
	v_fmac_f32_e32 v143, v142, v141
	v_mov_b32_e32 v142, 1.0
	v_mov_b32_e32 v150, v1
	v_mov_b32_e32 v151, 1.0
	v_mov_b32_dpp v142, v146 row_shr:1 row_mask:0xf bank_mask:0xf
	v_mov_b32_dpp v150, v143 row_shr:1 row_mask:0xf bank_mask:0xf
	v_fma_f32 v150, v146, v150, v143
	v_mul_f32_e32 v142, v146, v142
	v_mov_b32_e32 v152, v1
	s_nop 0
	v_mov_b32_dpp v151, v142 row_shr:2 row_mask:0xf bank_mask:0xf
	v_mov_b32_dpp v152, v150 row_shr:2 row_mask:0xf bank_mask:0xf
	v_fmac_f32_e32 v150, v142, v152
	v_mul_f32_e32 v142, v142, v151
	v_mov_b32_e32 v151, 1.0
	v_mov_b32_e32 v152, v1
	s_nop 0
	v_mov_b32_dpp v151, v142 row_shr:4 row_mask:0xf bank_mask:0xf
	v_mov_b32_dpp v152, v150 row_shr:4 row_mask:0xf bank_mask:0xf
	v_fmac_f32_e32 v150, v142, v152
	v_mul_f32_e32 v142, v142, v151
	v_mov_b32_e32 v151, 1.0
	v_mov_b32_e32 v152, v1
	s_nop 0
	v_mov_b32_dpp v151, v142 row_shr:8 row_mask:0xf bank_mask:0xf
	v_mov_b32_dpp v152, v150 row_shr:8 row_mask:0xf bank_mask:0xf
	v_fmac_f32_e32 v150, v142, v152
	v_mul_f32_e32 v142, v142, v151
	v_mov_b32_e32 v151, 1.0
	v_mov_b32_dpp v161, v150 row_shr:1 row_mask:0xf bank_mask:0xf
	v_fmac_f32_e32 v150, 0, v142
	v_mov_b32_dpp v151, v142 row_shr:1 row_mask:0xf bank_mask:0xf
	v_fmac_f32_e32 v161, 0, v151
	ds_bpermute_b32 v225, v196, v150
	ds_read_b128 v[150:153], v226
	v_fmac_f32_e32 v145, v144, v161
	v_fmac_f32_e32 v149, v148, v161
	v_fmac_f32_e32 v147, v154, v161
	v_fmac_f32_e32 v141, v140, v161
	s_waitcnt lgkmcnt(0)
	v_lshlrev_b32_e32 v163, 16, v152
	v_lshlrev_b32_e32 v142, 16, v150
	v_mul_f32_e32 v144, v145, v163
	v_mul_f32_e32 v145, 0xbfb8aa3b, v163
	v_mul_f32_e32 v148, v149, v142
	v_mul_f32_e32 v142, 0xbfb8aa3b, v142
	v_exp_f32_e32 v145, v145
	v_exp_f32_e32 v142, v142
	v_and_b32_e32 v150, 0xffff0000, v150
	v_and_b32_e32 v152, 0xffff0000, v152
	v_add_f32_e32 v145, 1.0, v145
	v_add_f32_e32 v142, 1.0, v142
	v_rcp_f32_e32 v145, v145
	v_rcp_f32_e32 v142, v142
	v_lshlrev_b32_e32 v164, 16, v153
	v_lshlrev_b32_e32 v162, 16, v151
	v_fmac_f32_e32 v156, v157, v161
	v_mul_f32_e32 v149, 0xbfb8aa3b, v150
	v_mul_f32_e32 v144, v144, v145
	v_mul_f32_e32 v145, v147, v152
	v_mul_f32_e32 v147, 0xbfb8aa3b, v152
	v_mul_f32_e32 v140, v141, v164
	v_mul_f32_e32 v141, 0xbfb8aa3b, v164
	v_mul_f32_e32 v142, v148, v142
	v_mul_f32_e32 v148, v156, v150
	v_exp_f32_e32 v149, v149
	v_mul_f32_e32 v150, 0xbfb8aa3b, v162
	v_exp_f32_e32 v147, v147
	v_exp_f32_e32 v141, v141
	v_exp_f32_e32 v150, v150
	v_add_f32_e32 v149, 1.0, v149
	v_add_f32_e32 v147, 1.0, v147
	v_add_f32_e32 v141, 1.0, v141
	v_rcp_f32_e32 v149, v149
	v_add_f32_e32 v150, 1.0, v150
	v_rcp_f32_e32 v147, v147
	v_rcp_f32_e32 v141, v141
	v_rcp_f32_e32 v150, v150
	v_and_b32_e32 v153, 0xffff0000, v153
	v_fmac_f32_e32 v158, v159, v161
	v_and_b32_e32 v151, 0xffff0000, v151
	v_mul_f32_e32 v148, v148, v149
	v_mul_f32_e32 v149, v158, v162
	v_fmac_f32_e32 v155, v160, v161
	v_mul_f32_e32 v145, v145, v147
	v_mul_f32_e32 v147, v140, v141
	v_mul_f32_e32 v141, 0xbfb8aa3b, v153
	v_mul_f32_e32 v149, v149, v150
	v_mul_f32_e32 v150, v155, v151
	v_mul_f32_e32 v151, 0xbfb8aa3b, v151
	v_exp_f32_e32 v141, v141
	v_exp_f32_e32 v151, v151
	v_fmac_f32_e32 v143, v146, v161
	v_mul_f32_e32 v140, v143, v153
	v_add_f32_e32 v141, 1.0, v141
	v_add_f32_e32 v151, 1.0, v151
	v_rcp_f32_e32 v141, v141
	v_rcp_f32_e32 v151, v151
	v_mul_f32_e32 v143, v140, v141
	v_mul_f32_e32 v150, v150, v151
	v_cvt_pk_bf16_f32 v140, v142, v148
	v_cvt_pk_bf16_f32 v141, v149, v150
	v_cvt_pk_bf16_f32 v142, v144, v145
	v_cvt_pk_bf16_f32 v143, v147, v143
	ds_write_b128 v227, v[140:143]
	s_waitcnt vmcnt(5)
	ds_write_b128 v177, v[124:127] offset:816
	s_waitcnt vmcnt(4)
	ds_write_b128 v179, v[128:131] offset:816
	s_waitcnt vmcnt(3)
	ds_write_b128 v181, v[132:135] offset:816
	s_waitcnt vmcnt(2)
	ds_write_b128 v199, v[136:139] offset:816
	s_and_saveexec_b64 s[10:11], s[38:39]
	ds_write_b128 v177, v[116:119]
	s_or_b64 exec, exec, s[10:11]
	s_lshl_b32 s7, s22, 3
	s_lshl_b32 s6, s23, 8
	s_and_b32 s7, s7, 0xc0
	s_or_b32 s6, s7, s6
	s_add_u32 s6, s6, s20
	s_addc_u32 s7, 0, s21
	v_and_b32_e32 v0, 3, v182
	v_lshl_add_u64 v[124:125], s[6:7], 0, v[184:185]
	v_lshlrev_b32_e32 v0, 4, v0
	v_lshl_add_u64 v[124:125], v[124:125], 0, v[0:1]
	v_mul_u32_u24_e32 v228, 0x110, v183
	v_lshl_add_u64 v[182:183], s[16:17], 0, v[124:125]
	s_movk_i32 s20, 0x100
	s_waitcnt vmcnt(0)
	v_readfirstlane_b32 s100, v172
	v_readfirstlane_b32 s101, v173
	v_and_b32_e32 v0, 15, v186
	v_lshlrev_b32_e32 v0, 4, v0
	v_subrev_u32_e32 v2, s100, v2
	v_lshl_add_u32 v2, v168, 11, v2
	v_lshl_or_b32 v174, v174, 11, v0
	v_lshl_or_b32 v176, v176, 11, v0
	v_lshl_or_b32 v178, v178, 11, v0
	v_lshl_or_b32 v180, v180, 11, v0
	v_add_u32_e32 v0, v171, v228
	s_add_u32 s100, s100, 0x80000
	s_addc_u32 s101, s101, 0
	s_sub_u32 s6, s100, 0x1800
	s_subb_u32 s7, s101, 0
	global_load_dwordx4 v[124:127], v174, s[100:101]
	global_load_dwordx4 v[128:131], v176, s[100:101]
	global_load_dwordx4 v[132:135], v178, s[100:101]
	global_load_dwordx4 v[136:139], v180, s[100:101]
	s_and_saveexec_b64 s[10:11], s[38:39]
	s_cbranch_execz .Lrnn_pre_halo
	global_load_dwordx4 v[116:119], v174, s[6:7]
.Lrnn_pre_halo:
	s_or_b64 exec, exec, s[10:11]
	s_branch .LBB0_113
.LBB0_112:
	s_or_b64 exec, exec, s[10:11]
	s_addk_i32 s20, 0x80
	s_mov_b64 s[6:7], 0x80000
	s_cmpk_lg_i32 s20, 0x1080
	v_lshl_add_u64 v[182:183], v[182:183], 0, s[6:7]
	s_cbranch_scc0 .LBB0_84
.LBB0_113:
	s_waitcnt lgkmcnt(0)
	s_barrier
	ds_read_b128 v[140:143], v204
	ds_read_b128 v[190:193], v205
	ds_read_b128 v[238:241], v205 offset:16
	ds_read_b128 v[160:163], v204 offset:64
	ds_read_b128 v[242:245], v205 offset:32
	ds_read_b128 v[246:249], v205 offset:48
	ds_read_u16 v148, v0
	ds_read_u16 v152, v0 offset:272
	ds_read_u16 v149, v0 offset:544
	ds_read_u16 v153, v0 offset:816
	ds_read_u16 v150, v0 offset:1088
	ds_read_u16 v154, v0 offset:1360
	ds_read_u16 v151, v0 offset:1632
	ds_read_u16 v155, v0 offset:1904
	s_waitcnt lgkmcnt(12)
	v_mfma_f32_16x16x32_bf16 v[140:143], v[4:7], v[190:193], v[140:143]
	s_waitcnt lgkmcnt(9)
	v_mfma_f32_16x16x32_bf16 v[160:163], v[12:15], v[242:245], v[160:163]
	v_mfma_f32_16x16x32_bf16 v[140:143], v[8:11], v[238:241], v[140:143]
	s_waitcnt lgkmcnt(8)
	v_mfma_f32_16x16x32_bf16 v[160:163], v[16:19], v[246:249], v[160:163]
	ds_read_b128 v[200:203], v204 offset:128
	ds_read_b128 v[190:193], v205 offset:64
	ds_read_b128 v[238:241], v205 offset:80
	ds_read_b128 v[164:167], v204 offset:192
	ds_read_b128 v[242:245], v205 offset:96
	ds_read_b128 v[246:249], v205 offset:112
	s_waitcnt lgkmcnt(6)
	v_perm_b32 v149, v153, v149, s8
	v_perm_b32 v148, v152, v148, s8
	v_perm_b32 v150, v154, v150, s8
	v_perm_b32 v151, v155, v151, s8
	s_cmp_eq_u64 s[38:39], 0
	s_cbranch_scc0 .Lrnn_w0
	s_waitcnt vmcnt(5)
	s_branch .Lrnn_wd

.Lrnn_wd:
	ds_write_b16 v175, v120
	ds_write_b16_d16_hi v175, v120 offset:272
	ds_write_b16 v175, v121 offset:544
	ds_write_b16_d16_hi v175, v121 offset:816
	ds_write_b16 v175, v122 offset:1088
	ds_write_b16_d16_hi v175, v122 offset:1360
	ds_write_b16 v175, v123 offset:1632
	ds_write_b16_d16_hi v175, v123 offset:1904
	s_nop 0
	global_load_dwordx4 v[120:123], v2, s[100:101]
	global_store_dwordx4 v[182:183], v[148:151], off
	v_cvt_pk_bf16_f32 v140, v140, v141
	v_cvt_pk_bf16_f32 v141, v142, v143
	v_cvt_pk_bf16_f32 v142, v160, v161
	v_cvt_pk_bf16_f32 v143, v162, v163
	v_cndmask_b32_e32 v229, 0, v140, vcc
	v_cndmask_b32_e32 v230, 0, v141, vcc
	v_mfma_f32_16x16x32_bf16 v[156:159], v[52:55], v[140:143], 0
	v_cndmask_b32_e32 v184, 0, v142, vcc
	v_cndmask_b32_e32 v185, 0, v143, vcc
	v_mfma_f32_16x16x32_bf16 v[144:147], v[68:71], v[140:143], 0
	v_mfma_f32_16x16x32_bf16 v[148:151], v[84:87], v[140:143], 0
	v_mfma_f32_16x16x32_bf16 v[152:155], v[100:103], v[140:143], 0
	s_waitcnt lgkmcnt(12)
	v_mfma_f32_16x16x32_bf16 v[200:203], v[20:23], v[190:193], v[200:203]
	s_waitcnt lgkmcnt(9)
	v_mfma_f32_16x16x32_bf16 v[164:167], v[28:31], v[242:245], v[164:167]
	v_mfma_f32_16x16x32_bf16 v[200:203], v[24:27], v[238:241], v[200:203]
	s_waitcnt lgkmcnt(0)
	v_mfma_f32_16x16x32_bf16 v[164:167], v[32:35], v[246:249], v[164:167]
	ds_read_b128 v[140:143], v204 offset:256
	ds_read_b128 v[190:193], v205 offset:128
	ds_read_b128 v[238:241], v205 offset:144
	ds_read_b128 v[160:163], v204 offset:320
	ds_read_b128 v[242:245], v205 offset:160
	ds_read_b128 v[246:249], v205 offset:176
	ds_read_b128 v[214:217], v206
	ds_read_b128 v[218:221], v207
	s_nop 1
	v_cvt_pk_bf16_f32 v200, v200, v201
	v_cvt_pk_bf16_f32 v201, v202, v203
	v_cvt_pk_bf16_f32 v202, v164, v165
	v_cvt_pk_bf16_f32 v203, v166, v167
	v_cndmask_b32_e64 v229, v229, v200, s[40:41]
	v_cndmask_b32_e64 v230, v230, v201, s[40:41]
	v_mfma_f32_16x16x32_bf16 v[156:159], v[56:59], v[200:203], v[156:159]
	v_cndmask_b32_e64 v184, v184, v202, s[40:41]
	v_cndmask_b32_e64 v185, v185, v203, s[40:41]
	v_mfma_f32_16x16x32_bf16 v[144:147], v[72:75], v[200:203], v[144:147]
	v_mfma_f32_16x16x32_bf16 v[148:151], v[88:91], v[200:203], v[148:151]
	v_mfma_f32_16x16x32_bf16 v[152:155], v[104:107], v[200:203], v[152:155]
	s_waitcnt lgkmcnt(6)
	v_mfma_f32_16x16x32_bf16 v[140:143], v[36:39], v[190:193], v[140:143]
	s_waitcnt lgkmcnt(3)
	v_mfma_f32_16x16x32_bf16 v[160:163], v[44:47], v[242:245], v[160:163]
	v_mfma_f32_16x16x32_bf16 v[140:143], v[40:43], v[238:241], v[140:143]
	s_waitcnt lgkmcnt(2)
	v_mfma_f32_16x16x32_bf16 v[160:163], v[48:51], v[246:249], v[160:163]
	ds_read_b128 v[200:203], v204 offset:384
	ds_read_b128 v[190:193], v205 offset:192
	ds_read_b128 v[238:241], v205 offset:208
	ds_read_b128 v[164:167], v204 offset:448
	ds_read_b128 v[242:245], v205 offset:224
	ds_read_b128 v[246:249], v205 offset:240
	s_nop 3
	v_cvt_pk_bf16_f32 v140, v140, v141
	v_cvt_pk_bf16_f32 v141, v142, v143
	v_cvt_pk_bf16_f32 v142, v160, v161
	v_cvt_pk_bf16_f32 v143, v162, v163
	v_cndmask_b32_e64 v229, v229, v140, s[42:43]
	v_cndmask_b32_e64 v230, v230, v141, s[42:43]
	v_mfma_f32_16x16x32_bf16 v[156:159], v[60:63], v[140:143], v[156:159]
	v_cndmask_b32_e64 v184, v184, v142, s[42:43]
	v_cndmask_b32_e64 v185, v185, v143, s[42:43]
	v_mfma_f32_16x16x32_bf16 v[144:147], v[76:79], v[140:143], v[144:147]
	v_mfma_f32_16x16x32_bf16 v[148:151], v[92:95], v[140:143], v[148:151]
	v_mfma_f32_16x16x32_bf16 v[152:155], v[108:111], v[140:143], v[152:155]
	ds_read_b128 v[140:143], v208
	ds_read_b128 v[160:163], v209
	s_waitcnt lgkmcnt(6)
	v_mfma_f32_16x16x32_bf16 v[200:203], v[214:217], v[190:193], v[200:203]
	s_waitcnt lgkmcnt(3)
	v_mfma_f32_16x16x32_bf16 v[164:167], v[218:221], v[242:245], v[164:167]
	s_waitcnt lgkmcnt(1)
	v_mfma_f32_16x16x32_bf16 v[200:203], v[140:143], v[238:241], v[200:203]
	s_waitcnt lgkmcnt(0)
	v_mfma_f32_16x16x32_bf16 v[164:167], v[160:163], v[246:249], v[164:167]
	ds_read_b128 v[190:193], v210
	ds_read_b128 v[238:241], v210 offset:128
	ds_read_b128 v[242:245], v210 offset:256
	ds_read_b128 v[246:249], v210 offset:64
	ds_read_b128 v[214:217], v210 offset:192
	ds_read_b128 v[218:221], v210 offset:320
	s_nop 3
	v_cvt_pk_bf16_f32 v200, v200, v201
	v_cvt_pk_bf16_f32 v201, v202, v203
	v_cvt_pk_bf16_f32 v202, v164, v165
	v_cvt_pk_bf16_f32 v203, v166, v167
	v_cndmask_b32_e64 v229, v229, v200, s[44:45]
	v_cndmask_b32_e64 v230, v230, v201, s[44:45]
	v_mfma_f32_16x16x32_bf16 v[156:159], v[64:67], v[200:203], v[156:159]
	v_cndmask_b32_e64 v184, v184, v202, s[44:45]
	v_cndmask_b32_e64 v185, v185, v203, s[44:45]
	v_mfma_f32_16x16x32_bf16 v[144:147], v[80:83], v[200:203], v[144:147]
	v_mfma_f32_16x16x32_bf16 v[148:151], v[96:99], v[200:203], v[148:151]
	v_mfma_f32_16x16x32_bf16 v[152:155], v[112:115], v[200:203], v[152:155]
	v_lshlrev_b32_e32 v231, 16, v229
	v_and_b32_e32 v229, 0xffff0000, v229
	v_lshlrev_b32_e32 v232, 16, v230
	v_and_b32_e32 v230, 0xffff0000, v230
	v_lshlrev_b32_e32 v228, 16, v184
	v_and_b32_e32 v184, 0xffff0000, v184
	v_lshlrev_b32_e32 v3, 16, v185
	v_and_b32_e32 v185, 0xffff0000, v185
	s_nop 1
	s_waitcnt lgkmcnt(5)
	v_add_f32_e32 v156, v156, v190
	v_add_f32_e32 v157, v157, v191
	v_add_f32_e32 v158, v158, v192
	v_add_f32_e32 v159, v159, v193
	s_waitcnt lgkmcnt(4)
	v_add_f32_e32 v148, v148, v238
	v_add_f32_e32 v149, v149, v239
	v_add_f32_e32 v150, v150, v240
	v_add_f32_e32 v151, v151, v241
	v_exp_f32_e32 v156, v156
	v_exp_f32_e32 v157, v157
	v_exp_f32_e32 v158, v158
	v_exp_f32_e32 v159, v159
	v_exp_f32_e32 v148, v148
	v_exp_f32_e32 v149, v149
	v_exp_f32_e32 v150, v150
	v_exp_f32_e32 v151, v151
	s_waitcnt lgkmcnt(2)
	v_add_f32_e32 v144, v144, v246
	v_add_f32_e32 v145, v145, v247
	v_add_f32_e32 v146, v146, v248
	v_add_f32_e32 v147, v147, v249
	s_waitcnt lgkmcnt(1)
	v_add_f32_e32 v152, v152, v214
	v_add_f32_e32 v153, v153, v215
	v_add_f32_e32 v154, v154, v216
	v_add_f32_e32 v155, v155, v217
	v_exp_f32_e32 v144, v144
	v_exp_f32_e32 v145, v145
	v_exp_f32_e32 v146, v146
	v_exp_f32_e32 v147, v147
	v_exp_f32_e32 v152, v152
	v_exp_f32_e32 v153, v153
	v_exp_f32_e32 v154, v154
	v_exp_f32_e32 v155, v155
	v_add_f32_e32 v156, 1.0, v156
	v_add_f32_e32 v157, 1.0, v157
	v_add_f32_e32 v158, 1.0, v158
	v_add_f32_e32 v159, 1.0, v159
	v_add_f32_e32 v144, 1.0, v144
	v_add_f32_e32 v145, 1.0, v145
	v_add_f32_e32 v146, 1.0, v146
	v_add_f32_e32 v147, 1.0, v147
	v_add_f32_e32 v148, 1.0, v148
	v_add_f32_e32 v149, 1.0, v149
	v_add_f32_e32 v150, 1.0, v150
	v_add_f32_e32 v151, 1.0, v151
	v_add_f32_e32 v152, 1.0, v152
	v_add_f32_e32 v153, 1.0, v153
	v_add_f32_e32 v154, 1.0, v154
	v_add_f32_e32 v155, 1.0, v155
	v_rcp_f32_e64 v156, -v156
	v_rcp_f32_e64 v157, -v157
	v_rcp_f32_e64 v158, -v158
	v_rcp_f32_e64 v159, -v159
	v_rcp_f32_e64 v144, -v144
	v_rcp_f32_e64 v145, -v145
	v_rcp_f32_e64 v146, -v146
	v_rcp_f32_e64 v147, -v147
	v_rcp_f32_e32 v148, v148
	v_rcp_f32_e32 v149, v149
	v_rcp_f32_e32 v150, v150
	v_rcp_f32_e32 v151, v151
	v_rcp_f32_e32 v152, v152
	v_rcp_f32_e32 v153, v153
	v_rcp_f32_e32 v154, v154
	v_rcp_f32_e32 v155, v155
	s_waitcnt lgkmcnt(0)
	v_mul_f32_e32 v156, v242, v156
	v_mul_f32_e32 v157, v243, v157
	v_mul_f32_e32 v158, v244, v158
	v_mul_f32_e32 v159, v245, v159
	v_mul_f32_e32 v144, v218, v144
	v_mul_f32_e32 v145, v219, v145
	v_mul_f32_e32 v146, v220, v146
	v_mul_f32_e32 v147, v221, v147
	v_mul_f32_e32 v148, v148, v231
	v_mul_f32_e32 v149, v149, v229
	v_mul_f32_e32 v150, v150, v232
	v_mul_f32_e32 v151, v151, v230
	v_mul_f32_e32 v152, v152, v228
	v_mul_f32_e32 v153, v153, v184
	v_mul_f32_e32 v154, v154, v3
	v_mul_f32_e32 v155, v155, v185
	v_exp_f32_e32 v238, v156
	v_exp_f32_e32 v240, v157
	v_exp_f32_e32 v242, v158
	v_exp_f32_e32 v244, v159
	v_exp_f32_e32 v214, v144
	v_exp_f32_e32 v216, v145
	v_exp_f32_e32 v218, v146
	v_exp_f32_e32 v220, v147
	v_fma_f32 v190, -v238, v238, 1.0
	v_fma_f32 v191, -v240, v240, 1.0
	v_fma_f32 v192, -v242, v242, 1.0
	v_fma_f32 v193, -v244, v244, 1.0
	v_fma_f32 v246, -v214, v214, 1.0
	v_fma_f32 v247, -v216, v216, 1.0
	v_fma_f32 v248, -v218, v218, 1.0
	v_fma_f32 v249, -v220, v220, 1.0
	v_sqrt_f32_e32 v190, v190
	v_sqrt_f32_e32 v191, v191
	v_sqrt_f32_e32 v192, v192
	v_sqrt_f32_e32 v193, v193
	v_sqrt_f32_e32 v246, v246
	v_sqrt_f32_e32 v247, v247
	v_sqrt_f32_e32 v248, v248
	v_sqrt_f32_e32 v249, v249
	v_mul_f32_e32 v239, v148, v190
	v_mul_f32_e32 v241, v149, v191
	v_mul_f32_e32 v243, v150, v192
	v_mul_f32_e32 v245, v151, v193
	v_mul_f32_e32 v215, v152, v246
	v_mul_f32_e32 v217, v153, v247
	v_mul_f32_e32 v219, v154, v248
	v_mul_f32_e32 v221, v155, v249
	ds_write_b64 v213, v[238:239]
	ds_write_b64 v213, v[240:241] offset:1056
	ds_write_b64 v213, v[242:243] offset:2112
	ds_write_b64 v213, v[244:245] offset:3168
	ds_write_b64 v213, v[214:215] offset:16896
	ds_write_b64 v213, v[216:217] offset:17952
	ds_write_b64 v213, v[218:219] offset:19008
	ds_write_b64 v213, v[220:221] offset:20064
	v_mov_b32_e32 v161, 0
	s_waitcnt lgkmcnt(0)
	s_barrier
	ds_read_b128 v[148:151], v224
	ds_read_b128 v[152:155], v224 offset:16
	ds_read_b128 v[144:147], v224 offset:32
	ds_read_b128 v[140:143], v224 offset:48
	s_waitcnt vmcnt(2)
	ds_write_b128 v177, v[124:127] offset:816
	ds_write_b128 v179, v[128:131] offset:816
	ds_write_b128 v181, v[132:135] offset:816
	ds_write_b128 v199, v[136:139] offset:816
	s_and_saveexec_b64 s[10:11], s[38:39]
	s_cbranch_execz .Lrnn_halo_done
	ds_write_b128 v177, v[116:119]
.Lrnn_halo_done:
	s_or_b64 exec, exec, s[10:11]
	s_cmpk_eq_i32 s20, 0x1000
	s_cbranch_scc1 .Lrnn_halo_ld
	s_cmpk_lt_i32 s20, 0xf80
	s_cselect_b32 s7, 0x40000, 0
	s_add_u32 s100, s100, s7
	s_addc_u32 s101, s101, 0
	s_sub_u32 s6, s100, 0x1800
	s_subb_u32 s7, s101, 0
	global_load_dwordx4 v[124:127], v174, s[100:101]
	global_load_dwordx4 v[128:131], v176, s[100:101]
	global_load_dwordx4 v[132:135], v178, s[100:101]
	global_load_dwordx4 v[136:139], v180, s[100:101]
	s_and_saveexec_b64 s[10:11], s[38:39]
	s_cbranch_execz .Lrnn_halo_ld
	global_load_dwordx4 v[116:119], v174, s[6:7]
.Lrnn_halo_ld:
	s_or_b64 exec, exec, s[10:11]
	s_waitcnt lgkmcnt(7)
	v_fma_f32 v149, 0, v148, v149
	v_fma_f32 v156, v150, v149, v151
	v_mul_f32_e32 v157, v148, v150
	s_waitcnt lgkmcnt(6)
	v_fma_f32 v158, v152, v156, v153
	v_mul_f32_e32 v159, v157, v152
	v_mul_f32_e32 v160, v154, v159
	v_fmac_f32_e32 v155, v154, v158
	s_waitcnt lgkmcnt(5)
	v_fma_f32 v145, v144, v155, v145
	v_mul_f32_e32 v144, v144, v160
	v_mul_f32_e32 v154, v146, v144
	v_fmac_f32_e32 v147, v146, v145
	s_waitcnt lgkmcnt(4)
	v_fma_f32 v141, v140, v147, v141
	v_mul_f32_e32 v140, v140, v154
	v_mul_f32_e32 v146, v142, v140
	v_fmac_f32_e32 v143, v142, v141
	v_mov_b32_e32 v150, v143
	v_mov_b32_e32 v142, v146
	v_mov_b32_e32 v151, 1.0
	v_fmac_f32_dpp v150, v150, v142 row_shr:1 row_mask:0xf bank_mask:0xf
	v_mul_f32_dpp v142, v142, v142 row_shr:1 row_mask:0xf bank_mask:0xf
	s_nop 0
	v_fmac_f32_dpp v150, v150, v142 row_shr:2 row_mask:0xf bank_mask:0xf
	v_mul_f32_dpp v142, v142, v142 row_shr:2 row_mask:0xf bank_mask:0xf
	s_nop 0
	v_fmac_f32_dpp v150, v150, v142 row_shr:4 row_mask:0xf bank_mask:0xf
	v_mul_f32_dpp v142, v142, v142 row_shr:4 row_mask:0xf bank_mask:0xf
	s_nop 0
	v_fmac_f32_dpp v150, v150, v142 row_shr:8 row_mask:0xf bank_mask:0xf
	v_mul_f32_dpp v142, v142, v142 row_shr:8 row_mask:0xf bank_mask:0xf
	s_nop 0
	v_mov_b32_dpp v161, v150 row_shr:1 row_mask:0xf bank_mask:0xf
	v_mov_b32_dpp v151, v142 row_shr:1 row_mask:0xf bank_mask:0xf
	v_fmac_f32_e32 v150, v142, v225
	v_fmac_f32_e32 v161, v151, v225
	ds_bpermute_b32 v225, v196, v150
	ds_read_b128 v[150:153], v226
	v_fmac_f32_e32 v145, v144, v161
	v_fmac_f32_e32 v149, v148, v161
	v_fmac_f32_e32 v147, v154, v161
	v_fmac_f32_e32 v141, v140, v161
	s_waitcnt lgkmcnt(0)
	v_lshlrev_b32_e32 v163, 16, v152
	v_lshlrev_b32_e32 v142, 16, v150
	v_mul_f32_e32 v144, v145, v163
	v_mul_f32_e32 v145, 0xbfb8aa3b, v163
	v_mul_f32_e32 v148, v149, v142
	v_mul_f32_e32 v142, 0xbfb8aa3b, v142
	v_exp_f32_e32 v145, v145
	v_exp_f32_e32 v142, v142
	v_and_b32_e32 v150, 0xffff0000, v150
	v_and_b32_e32 v152, 0xffff0000, v152
	v_add_f32_e32 v145, 1.0, v145
	v_add_f32_e32 v142, 1.0, v142
	v_rcp_f32_e32 v145, v145
	v_rcp_f32_e32 v142, v142
	v_lshlrev_b32_e32 v164, 16, v153
	v_lshlrev_b32_e32 v162, 16, v151
	v_fmac_f32_e32 v156, v157, v161
	v_mul_f32_e32 v149, 0xbfb8aa3b, v150
	v_mul_f32_e32 v144, v144, v145
	v_mul_f32_e32 v145, v147, v152
	v_mul_f32_e32 v147, 0xbfb8aa3b, v152
	v_mul_f32_e32 v140, v141, v164
	v_mul_f32_e32 v141, 0xbfb8aa3b, v164
	v_mul_f32_e32 v142, v148, v142
	v_mul_f32_e32 v148, v156, v150
	v_exp_f32_e32 v149, v149
	v_mul_f32_e32 v150, 0xbfb8aa3b, v162
	v_exp_f32_e32 v147, v147
	v_exp_f32_e32 v141, v141
	v_exp_f32_e32 v150, v150
	v_add_f32_e32 v149, 1.0, v149
	v_add_f32_e32 v147, 1.0, v147
	v_add_f32_e32 v141, 1.0, v141
	v_rcp_f32_e32 v149, v149
	v_add_f32_e32 v150, 1.0, v150
	v_rcp_f32_e32 v147, v147
	v_rcp_f32_e32 v141, v141
	v_rcp_f32_e32 v150, v150
	v_and_b32_e32 v153, 0xffff0000, v153
	v_fmac_f32_e32 v158, v159, v161
	v_and_b32_e32 v151, 0xffff0000, v151
	v_mul_f32_e32 v148, v148, v149
	v_mul_f32_e32 v149, v158, v162
	v_fmac_f32_e32 v155, v160, v161
	v_mul_f32_e32 v145, v145, v147
	v_mul_f32_e32 v147, v140, v141
	v_mul_f32_e32 v141, 0xbfb8aa3b, v153
	v_mul_f32_e32 v149, v149, v150
	v_mul_f32_e32 v150, v155, v151
	v_mul_f32_e32 v151, 0xbfb8aa3b, v151
	v_exp_f32_e32 v141, v141
	v_exp_f32_e32 v151, v151
	v_fmac_f32_e32 v143, v146, v161
	v_mul_f32_e32 v140, v143, v153
	v_add_f32_e32 v141, 1.0, v141
	v_add_f32_e32 v151, 1.0, v151
	v_rcp_f32_e32 v141, v141
	v_rcp_f32_e32 v151, v151
	v_mul_f32_e32 v143, v140, v141
	v_mul_f32_e32 v150, v150, v151
	v_cvt_pk_bf16_f32 v140, v142, v148
	v_cvt_pk_bf16_f32 v141, v149, v150
	v_cvt_pk_bf16_f32 v142, v144, v145
	v_cvt_pk_bf16_f32 v143, v147, v143
	ds_write_b128 v227, v[140:143]
	s_branch .LBB0_112
